# G4 thin gate product: 24 loads per 8-k-step group issued together into two alternating register sets with counted waits (was a shallow load/wait ladder)
# speedup vs baseline: 1.0077x; 1.0077x over previous
; #define MFMA16(a, b, c) __builtin_amdgcn_mfma_f32_16x16x32_bf16((a), (b), (c), 0, 0, 0)
; DI void phase_g4(const Params& p, const Sub& s, char* lds_all) {
;     ...
;     for (int rt = blockIdx.x; rt < 256; rt += gridDim.x) {
;       const int r0 = rt * 256 + wid * 32;
;       const bf16_t* a0p = A + (size_t)(r0 + fr) * D + fq * 8;
;       const bf16_t* a1p = a0p + (size_t)16 * D;
;       const bf16_t* bp = Bt + (size_t)(3072 + fr) * D + fq * 8;
;       f32x4 c0 = (f32x4){0.f, 0.f, 0.f, 0.f}, c1 = (f32x4){0.f, 0.f, 0.f, 0.f};
; #pragma unroll 8
;       for (int ks = 0; ks < 32; ++ks) {
;         const bf16x8 bb = *(const bf16x8*)(bp + ks * 32);
;         const bf16x8 x0 = *(const bf16x8*)(a0p + ks * 32), x1 = *(const bf16x8*)(a1p + ks * 32);
;         c0 = MFMA16(bb, x0, c0); c1 = MFMA16(bb, x1, c1);
;       }
.LBB0_1178:
	v_add_co_u32_e32 v216, vcc, 0xe00000, v16
	s_nop 0
	v_addc_co_u32_e32 v217, vcc, 0, v17, vcc
	v_add_co_u32_e32 v218, vcc, 0x1800000, v18
	s_nop 0
	v_addc_co_u32_e32 v219, vcc, 0, v19, vcc
	v_add_co_u32_e32 v220, vcc, 0x1808000, v18
	s_nop 0
	v_addc_co_u32_e32 v221, vcc, 0, v19, vcc
	global_load_dwordx4 v[22:25], v[216:217], off
	global_load_dwordx4 v[26:29], v[218:219], off
	global_load_dwordx4 v[30:33], v[220:221], off
	global_load_dwordx4 v[34:37], v[216:217], off offset:64
	global_load_dwordx4 v[38:41], v[218:219], off offset:64
	global_load_dwordx4 v[42:45], v[220:221], off offset:64
	global_load_dwordx4 v[46:49], v[216:217], off offset:128
	global_load_dwordx4 v[50:53], v[218:219], off offset:128
	global_load_dwordx4 v[54:57], v[220:221], off offset:128
	global_load_dwordx4 v[58:61], v[216:217], off offset:192
	global_load_dwordx4 v[62:65], v[218:219], off offset:192
	global_load_dwordx4 v[66:69], v[220:221], off offset:192
	global_load_dwordx4 v[70:73], v[216:217], off offset:256
	global_load_dwordx4 v[74:77], v[218:219], off offset:256
	global_load_dwordx4 v[78:81], v[220:221], off offset:256
	global_load_dwordx4 v[82:85], v[216:217], off offset:320
	global_load_dwordx4 v[86:89], v[218:219], off offset:320
	global_load_dwordx4 v[90:93], v[220:221], off offset:320
	global_load_dwordx4 v[94:97], v[216:217], off offset:384
	global_load_dwordx4 v[98:101], v[218:219], off offset:384
	global_load_dwordx4 v[102:105], v[220:221], off offset:384
	global_load_dwordx4 v[106:109], v[216:217], off offset:448
	global_load_dwordx4 v[110:113], v[218:219], off offset:448
	global_load_dwordx4 v[114:117], v[220:221], off offset:448
	global_load_dwordx4 v[118:121], v[216:217], off offset:512
	global_load_dwordx4 v[122:125], v[218:219], off offset:512
	global_load_dwordx4 v[126:129], v[220:221], off offset:512
	global_load_dwordx4 v[130:133], v[216:217], off offset:576
	global_load_dwordx4 v[134:137], v[218:219], off offset:576
	global_load_dwordx4 v[138:141], v[220:221], off offset:576
	global_load_dwordx4 v[142:145], v[216:217], off offset:640
	global_load_dwordx4 v[146:149], v[218:219], off offset:640
	global_load_dwordx4 v[150:153], v[220:221], off offset:640
	global_load_dwordx4 v[154:157], v[216:217], off offset:704
	global_load_dwordx4 v[158:161], v[218:219], off offset:704
	global_load_dwordx4 v[162:165], v[220:221], off offset:704
	global_load_dwordx4 v[166:169], v[216:217], off offset:768
	global_load_dwordx4 v[170:173], v[218:219], off offset:768
	global_load_dwordx4 v[174:177], v[220:221], off offset:768
	global_load_dwordx4 v[178:181], v[216:217], off offset:832
	global_load_dwordx4 v[184:187], v[218:219], off offset:832
	global_load_dwordx4 v[188:191], v[220:221], off offset:832
	global_load_dwordx4 v[192:195], v[216:217], off offset:896
	global_load_dwordx4 v[196:199], v[218:219], off offset:896
	global_load_dwordx4 v[200:203], v[220:221], off offset:896
	global_load_dwordx4 v[204:207], v[216:217], off offset:960
	global_load_dwordx4 v[208:211], v[218:219], off offset:960
	global_load_dwordx4 v[212:215], v[220:221], off offset:960
	s_waitcnt vmcnt(24)
	v_mfma_f32_16x16x32_bf16 v[0:3], v[22:25], v[26:29], v[0:3]
	v_mfma_f32_16x16x32_bf16 v[4:7], v[22:25], v[30:33], v[4:7]
	v_mfma_f32_16x16x32_bf16 v[0:3], v[34:37], v[38:41], v[0:3]
	v_mfma_f32_16x16x32_bf16 v[4:7], v[34:37], v[42:45], v[4:7]
	v_mfma_f32_16x16x32_bf16 v[0:3], v[46:49], v[50:53], v[0:3]
	v_mfma_f32_16x16x32_bf16 v[4:7], v[46:49], v[54:57], v[4:7]
	v_mfma_f32_16x16x32_bf16 v[0:3], v[58:61], v[62:65], v[0:3]
	v_mfma_f32_16x16x32_bf16 v[4:7], v[58:61], v[66:69], v[4:7]
	v_mfma_f32_16x16x32_bf16 v[0:3], v[70:73], v[74:77], v[0:3]
	v_mfma_f32_16x16x32_bf16 v[4:7], v[70:73], v[78:81], v[4:7]
	v_mfma_f32_16x16x32_bf16 v[0:3], v[82:85], v[86:89], v[0:3]
	v_mfma_f32_16x16x32_bf16 v[4:7], v[82:85], v[90:93], v[4:7]
	v_mfma_f32_16x16x32_bf16 v[0:3], v[94:97], v[98:101], v[0:3]
	v_mfma_f32_16x16x32_bf16 v[4:7], v[94:97], v[102:105], v[4:7]
	v_mfma_f32_16x16x32_bf16 v[0:3], v[106:109], v[110:113], v[0:3]
	v_mfma_f32_16x16x32_bf16 v[4:7], v[106:109], v[114:117], v[4:7]
	global_load_dwordx4 v[22:25], v[216:217], off offset:1024
	global_load_dwordx4 v[26:29], v[218:219], off offset:1024
	global_load_dwordx4 v[30:33], v[220:221], off offset:1024
	global_load_dwordx4 v[34:37], v[216:217], off offset:1088
	global_load_dwordx4 v[38:41], v[218:219], off offset:1088
	global_load_dwordx4 v[42:45], v[220:221], off offset:1088
	global_load_dwordx4 v[46:49], v[216:217], off offset:1152
	global_load_dwordx4 v[50:53], v[218:219], off offset:1152
	global_load_dwordx4 v[54:57], v[220:221], off offset:1152
	global_load_dwordx4 v[58:61], v[216:217], off offset:1216
	global_load_dwordx4 v[62:65], v[218:219], off offset:1216
	global_load_dwordx4 v[66:69], v[220:221], off offset:1216
	global_load_dwordx4 v[70:73], v[216:217], off offset:1280
	global_load_dwordx4 v[74:77], v[218:219], off offset:1280
	global_load_dwordx4 v[78:81], v[220:221], off offset:1280
	global_load_dwordx4 v[82:85], v[216:217], off offset:1344
	global_load_dwordx4 v[86:89], v[218:219], off offset:1344
	global_load_dwordx4 v[90:93], v[220:221], off offset:1344
	global_load_dwordx4 v[94:97], v[216:217], off offset:1408
	global_load_dwordx4 v[98:101], v[218:219], off offset:1408
	global_load_dwordx4 v[102:105], v[220:221], off offset:1408
	global_load_dwordx4 v[106:109], v[216:217], off offset:1472
	global_load_dwordx4 v[110:113], v[218:219], off offset:1472
	global_load_dwordx4 v[114:117], v[220:221], off offset:1472
	s_waitcnt vmcnt(24)
; #define MFMA16(a, b, c) __builtin_amdgcn_mfma_f32_16x16x32_bf16((a), (b), (c), 0, 0, 0)
; DI void phase_g4(const Params& p, const Sub& s, char* lds_all) {
;     ...
;       for (int ks = 0; ks < 32; ++ks) {
;         const bf16x8 bb = *(const bf16x8*)(bp + ks * 32);
;         const bf16x8 x0 = *(const bf16x8*)(a0p + ks * 32), x1 = *(const bf16x8*)(a1p + ks * 32);
;         c0 = MFMA16(bb, x0, c0); c1 = MFMA16(bb, x1, c1);
;       }
;       *(f32x4*)(ba + (size_t)(r0 + fr) * 16 + 4 * fq) = c0;
;       *(f32x4*)(ba + (size_t)(r0 + 16 + fr) * 16 + 4 * fq) = c1;
;     }
	v_mfma_f32_16x16x32_bf16 v[0:3], v[118:121], v[122:125], v[0:3]
	v_mfma_f32_16x16x32_bf16 v[4:7], v[118:121], v[126:129], v[4:7]
	v_mfma_f32_16x16x32_bf16 v[0:3], v[130:133], v[134:137], v[0:3]
	v_mfma_f32_16x16x32_bf16 v[4:7], v[130:133], v[138:141], v[4:7]
	v_mfma_f32_16x16x32_bf16 v[0:3], v[142:145], v[146:149], v[0:3]
	v_mfma_f32_16x16x32_bf16 v[4:7], v[142:145], v[150:153], v[4:7]
	v_mfma_f32_16x16x32_bf16 v[0:3], v[154:157], v[158:161], v[0:3]
	v_mfma_f32_16x16x32_bf16 v[4:7], v[154:157], v[162:165], v[4:7]
	v_mfma_f32_16x16x32_bf16 v[0:3], v[166:169], v[170:173], v[0:3]
	v_mfma_f32_16x16x32_bf16 v[4:7], v[166:169], v[174:177], v[4:7]
	v_mfma_f32_16x16x32_bf16 v[0:3], v[178:181], v[184:187], v[0:3]
	v_mfma_f32_16x16x32_bf16 v[4:7], v[178:181], v[188:191], v[4:7]
	v_mfma_f32_16x16x32_bf16 v[0:3], v[192:195], v[196:199], v[0:3]
	v_mfma_f32_16x16x32_bf16 v[4:7], v[192:195], v[200:203], v[4:7]
	v_mfma_f32_16x16x32_bf16 v[0:3], v[204:207], v[208:211], v[0:3]
	v_mfma_f32_16x16x32_bf16 v[4:7], v[204:207], v[212:215], v[4:7]
	global_load_dwordx4 v[118:121], v[216:217], off offset:1536
	global_load_dwordx4 v[122:125], v[218:219], off offset:1536
	global_load_dwordx4 v[126:129], v[220:221], off offset:1536
	global_load_dwordx4 v[130:133], v[216:217], off offset:1600
	global_load_dwordx4 v[134:137], v[218:219], off offset:1600
	global_load_dwordx4 v[138:141], v[220:221], off offset:1600
	global_load_dwordx4 v[142:145], v[216:217], off offset:1664
	global_load_dwordx4 v[146:149], v[218:219], off offset:1664
	global_load_dwordx4 v[150:153], v[220:221], off offset:1664
	global_load_dwordx4 v[154:157], v[216:217], off offset:1728
	global_load_dwordx4 v[158:161], v[218:219], off offset:1728
	global_load_dwordx4 v[162:165], v[220:221], off offset:1728
	global_load_dwordx4 v[166:169], v[216:217], off offset:1792
	global_load_dwordx4 v[170:173], v[218:219], off offset:1792
	global_load_dwordx4 v[174:177], v[220:221], off offset:1792
	global_load_dwordx4 v[178:181], v[216:217], off offset:1856
	global_load_dwordx4 v[184:187], v[218:219], off offset:1856
	global_load_dwordx4 v[188:191], v[220:221], off offset:1856
	global_load_dwordx4 v[192:195], v[216:217], off offset:1920
	global_load_dwordx4 v[196:199], v[218:219], off offset:1920
	global_load_dwordx4 v[200:203], v[220:221], off offset:1920
	global_load_dwordx4 v[204:207], v[216:217], off offset:1984
	global_load_dwordx4 v[208:211], v[218:219], off offset:1984
	global_load_dwordx4 v[212:215], v[220:221], off offset:1984
	s_waitcnt vmcnt(24)
	v_mfma_f32_16x16x32_bf16 v[0:3], v[22:25], v[26:29], v[0:3]
	v_mfma_f32_16x16x32_bf16 v[4:7], v[22:25], v[30:33], v[4:7]
	v_mfma_f32_16x16x32_bf16 v[0:3], v[34:37], v[38:41], v[0:3]
	v_mfma_f32_16x16x32_bf16 v[4:7], v[34:37], v[42:45], v[4:7]
	v_mfma_f32_16x16x32_bf16 v[0:3], v[46:49], v[50:53], v[0:3]
	v_mfma_f32_16x16x32_bf16 v[4:7], v[46:49], v[54:57], v[4:7]
	v_mfma_f32_16x16x32_bf16 v[0:3], v[58:61], v[62:65], v[0:3]
	v_mfma_f32_16x16x32_bf16 v[4:7], v[58:61], v[66:69], v[4:7]
	v_mfma_f32_16x16x32_bf16 v[0:3], v[70:73], v[74:77], v[0:3]
	v_mfma_f32_16x16x32_bf16 v[4:7], v[70:73], v[78:81], v[4:7]
	v_mfma_f32_16x16x32_bf16 v[0:3], v[82:85], v[86:89], v[0:3]
	v_mfma_f32_16x16x32_bf16 v[4:7], v[82:85], v[90:93], v[4:7]
	v_mfma_f32_16x16x32_bf16 v[0:3], v[94:97], v[98:101], v[0:3]
	v_mfma_f32_16x16x32_bf16 v[4:7], v[94:97], v[102:105], v[4:7]
	v_mfma_f32_16x16x32_bf16 v[0:3], v[106:109], v[110:113], v[0:3]
	v_mfma_f32_16x16x32_bf16 v[4:7], v[106:109], v[114:117], v[4:7]
	s_waitcnt vmcnt(0)
	v_mfma_f32_16x16x32_bf16 v[0:3], v[118:121], v[122:125], v[0:3]
	v_mfma_f32_16x16x32_bf16 v[4:7], v[118:121], v[126:129], v[4:7]
	v_mfma_f32_16x16x32_bf16 v[0:3], v[130:133], v[134:137], v[0:3]
	v_mfma_f32_16x16x32_bf16 v[4:7], v[130:133], v[138:141], v[4:7]
	v_mfma_f32_16x16x32_bf16 v[0:3], v[142:145], v[146:149], v[0:3]
	v_mfma_f32_16x16x32_bf16 v[4:7], v[142:145], v[150:153], v[4:7]
	v_mfma_f32_16x16x32_bf16 v[0:3], v[154:157], v[158:161], v[0:3]
	v_mfma_f32_16x16x32_bf16 v[4:7], v[154:157], v[162:165], v[4:7]
	v_mfma_f32_16x16x32_bf16 v[0:3], v[166:169], v[170:173], v[0:3]
	v_mfma_f32_16x16x32_bf16 v[4:7], v[166:169], v[174:177], v[4:7]
	v_mfma_f32_16x16x32_bf16 v[0:3], v[178:181], v[184:187], v[0:3]
	v_mfma_f32_16x16x32_bf16 v[4:7], v[178:181], v[188:191], v[4:7]
	v_mfma_f32_16x16x32_bf16 v[0:3], v[192:195], v[196:199], v[0:3]
	v_mfma_f32_16x16x32_bf16 v[4:7], v[192:195], v[200:203], v[4:7]
	v_mfma_f32_16x16x32_bf16 v[0:3], v[204:207], v[208:211], v[0:3]
	v_mfma_f32_16x16x32_bf16 v[4:7], v[204:207], v[212:215], v[4:7]
	v_lshl_add_u32 v18, s3, 8, v20
	v_ashrrev_i32_e32 v19, 31, v18
	v_lshlrev_b64 v[22:23], 6, v[18:19]
	v_lshl_add_u64 v[22:23], v[10:11], 0, v[22:23]
	s_nop 0
	global_store_dwordx4 v[22:23], v[0:3], off
	v_readlane_b32 s0, v251, 1
	s_add_i32 s3, s3, s0
	v_or_b32_e32 v0, 16, v18
	v_ashrrev_i32_e32 v1, 31, v0
	v_lshlrev_b64 v[0:1], 6, v[0:1]
	v_lshl_add_u64 v[0:1], v[10:11], 0, v[0:1]
	s_cmpk_gt_i32 s3, 0xff
	v_add_u32_e32 v14, s2, v14
	global_store_dwordx4 v[0:1], v[4:7], off
	v_readlane_b32 s1, v251, 2
	s_cbranch_scc0 .LBB0_1177
